# topk candidate stage regrouped: small sorted chains merged with pad-pruned bitonic merges before the 16-wide merges (567 -> 483 VALU); on top of v076
# baseline (speedup 1.0000x reference)
.Ltk_merge:
	s_mov_b64 s[40:41], exec
	s_mov_b64 exec, s[12:13]
	v_mov_b32_e32 v2, v74
	v_mov_b32_e32 v3, v75
	v_mov_b32_e32 v4, v76
	v_mov_b32_e32 v5, v77
	v_mov_b32_e32 v6, v78
	v_mov_b32_e32 v7, v79
	v_mov_b32_e32 v8, v80
	v_mov_b32_e32 v9, v81
	v_mov_b32_e32 v10, v82
	v_mov_b32_e32 v11, v83
	v_mov_b32_e32 v12, v84
	v_mov_b32_e32 v13, v85
	v_mov_b32_e32 v14, v86
	v_mov_b32_e32 v15, v87
	v_mov_b32_e32 v16, v88
	v_mov_b32_e32 v17, v89
	v_mov_b32_e32 v18, v98
	v_mov_b32_e32 v19, v99
	v_mov_b32_e32 v20, v100
	v_mov_b32_e32 v21, v101
	v_mov_b32_e32 v22, v102
	v_mov_b32_e32 v23, v103
	v_mov_b32_e32 v24, v104
	v_mov_b32_e32 v25, v105
	v_mov_b32_e32 v26, v106
	v_mov_b32_e32 v27, v107
	v_mov_b32_e32 v28, v108
	v_mov_b32_e32 v29, v109
	v_mov_b32_e32 v30, v110
	v_mov_b32_e32 v31, v111
	v_mov_b32_e32 v32, v112
	v_mov_b32_e32 v33, v113
	v_add_u32_e32 v36, 0xffff8000, v36
	s_mov_b64 exec, s[40:41]
	v_and_b32_e32 v34, 63, v119
	v_and_b32_e32 v30, 0xffffff80, v30
	v_and_b32_e32 v31, 0xffffff80, v31
	v_and_b32_e32 v32, 0xffffff80, v32
	v_and_b32_e32 v33, 0xffffff80, v33
	v_and_b32_e32 v26, 0xffffff80, v26
	v_and_b32_e32 v27, 0xffffff80, v27
	v_and_b32_e32 v28, 0xffffff80, v28
	v_and_b32_e32 v29, 0xffffff80, v29
	v_and_b32_e32 v22, 0xffffff80, v22
	v_and_b32_e32 v23, 0xffffff80, v23
	v_and_b32_e32 v24, 0xffffff80, v24
	v_and_b32_e32 v25, 0xffffff80, v25
	v_and_b32_e32 v18, 0xffffff80, v18
	v_and_b32_e32 v19, 0xffffff80, v19
	v_and_b32_e32 v20, 0xffffff80, v20
	v_and_b32_e32 v21, 0xffffff80, v21
	v_and_b32_e32 v2, 0xffffff80, v2
	v_and_b32_e32 v3, 0xffffff80, v3
	v_and_b32_e32 v4, 0xffffff80, v4
	v_and_b32_e32 v5, 0xffffff80, v5
	v_and_b32_e32 v14, 0xffffff80, v14
	v_and_b32_e32 v15, 0xffffff80, v15
	v_and_b32_e32 v16, 0xffffff80, v16
	v_and_b32_e32 v17, 0xffffff80, v17
	v_and_b32_e32 v10, 0xffffff80, v10
	v_and_b32_e32 v11, 0xffffff80, v11
	v_and_b32_e32 v12, 0xffffff80, v12
	v_and_b32_e32 v13, 0xffffff80, v13
	v_and_b32_e32 v6, 0xffffff80, v6
	v_and_b32_e32 v7, 0xffffff80, v7
	v_and_b32_e32 v8, 0xffffff80, v8
	v_and_b32_e32 v9, 0xffffff80, v9
	v_add_f32_e32 v35, v32, v2
	v_and_or_b32 v35, v35, s78, 32
	v_add_f32_e32 v42, v32, v3
	v_and_or_b32 v42, v42, s78, 33
	v_add_f32_e32 v43, v32, v4
	v_and_or_b32 v43, v43, s78, 34
	v_add_f32_e32 v44, v32, v5
	v_and_or_b32 v44, v44, s78, 35
	v_add_f32_e32 v45, v32, v14
	v_and_or_b32 v45, v45, s78, 36
	v_add_f32_e32 v46, v27, v2
	v_and_b32_e32 v46, s78, v46
	v_or_b32_e32 v46, 0x50, v46
	v_add_f32_e32 v47, v28, v2
	v_and_b32_e32 v47, s78, v47
	v_or_b32_e32 v47, 0x60, v47
	v_add_f32_e32 v48, v29, v2
	v_and_b32_e32 v48, s78, v48
	v_or_b32_e32 v48, 0x70, v48
	v_add_f32_e32 v49, v22, v2
	v_and_b32_e32 v49, s78, v49
	v_or_b32_e32 v49, 0x80, v49
	v_add_f32_e32 v50, v23, v2
	v_and_b32_e32 v50, s78, v50
	v_or_b32_e32 v50, 0x90, v50
	v_add_f32_e32 v51, v24, v2
	v_and_b32_e32 v51, s78, v51
	v_or_b32_e32 v51, 0xa0, v51
	v_add_f32_e32 v52, v25, v2
	v_and_b32_e32 v52, s78, v52
	v_or_b32_e32 v52, 0xb0, v52
	v_add_f32_e32 v53, v18, v2
	v_and_b32_e32 v53, s78, v53
	v_or_b32_e32 v53, 0xc0, v53
	v_add_f32_e32 v54, v19, v2
	v_and_b32_e32 v54, s78, v54
	v_or_b32_e32 v54, 0xd0, v54
	v_add_f32_e32 v55, v20, v2
	v_and_b32_e32 v55, s78, v55
	v_or_b32_e32 v55, 0xe0, v55
	v_add_f32_e32 v56, v21, v2
	v_and_b32_e32 v56, s78, v56
	v_or_b32_e32 v56, 0xf0, v56
	v_max_f32_e32 v57, v35, v53
	v_min_f32_e32 v53, v35, v53
	v_max_f32_e32 v35, v42, v52
	v_min_f32_e32 v52, v42, v52
	v_max_f32_e32 v42, v43, v51
	v_min_f32_e32 v51, v43, v51
	v_max_f32_e32 v43, v44, v50
	v_min_f32_e32 v50, v44, v50
	v_max_f32_e32 v44, v45, v49
	v_min_f32_e32 v49, v45, v49
	v_max_f32_e32 v45, v56, v48
	v_min_f32_e32 v48, v56, v48
	v_max_f32_e32 v56, v55, v47
	v_min_f32_e32 v47, v55, v47
	v_max_f32_e32 v55, v54, v46
	v_min_f32_e32 v46, v54, v46
	v_max_f32_e32 v54, v57, v44
	v_min_f32_e32 v44, v57, v44
	v_max_f32_e32 v57, v35, v45
	v_min_f32_e32 v45, v35, v45
	v_max_f32_e32 v35, v42, v56
	v_min_f32_e32 v56, v42, v56
	v_max_f32_e32 v42, v43, v55
	v_min_f32_e32 v55, v43, v55
	v_max_f32_e32 v43, v53, v49
	v_min_f32_e32 v49, v53, v49
	v_max_f32_e32 v53, v52, v48
	v_min_f32_e32 v48, v52, v48
	v_max_f32_e32 v52, v51, v47
	v_min_f32_e32 v47, v51, v47
	v_max_f32_e32 v51, v50, v46
	v_min_f32_e32 v46, v50, v46
	v_max_f32_e32 v50, v54, v35
	v_min_f32_e32 v35, v54, v35
	v_max_f32_e32 v54, v57, v42
	v_min_f32_e32 v42, v57, v42
	v_max_f32_e32 v57, v44, v56
	v_min_f32_e32 v56, v44, v56
	v_max_f32_e32 v44, v45, v55
	v_min_f32_e32 v55, v45, v55
	v_max_f32_e32 v45, v43, v52
	v_min_f32_e32 v52, v43, v52
	v_max_f32_e32 v43, v53, v51
	v_min_f32_e32 v51, v53, v51
	v_max_f32_e32 v53, v49, v47
	v_min_f32_e32 v47, v49, v47
	v_max_f32_e32 v49, v48, v46
	v_min_f32_e32 v46, v48, v46
	v_max_f32_e32 v48, v50, v54
	v_min_f32_e32 v54, v50, v54
	v_max_f32_e32 v50, v35, v42
	v_min_f32_e32 v42, v35, v42
	v_max_f32_e32 v35, v57, v44
	v_min_f32_e32 v44, v57, v44
	v_max_f32_e32 v57, v56, v55
	v_min_f32_e32 v55, v56, v55
	v_max_f32_e32 v56, v45, v43
	v_min_f32_e32 v43, v45, v43
	v_max_f32_e32 v45, v52, v51
	v_min_f32_e32 v51, v52, v51
	v_max_f32_e32 v52, v53, v49
	v_min_f32_e32 v49, v53, v49
	v_max_f32_e32 v53, v47, v46
	v_min_f32_e32 v46, v47, v46
	v_add_f32_e32 v47, v26, v2
	v_and_or_b32 v47, v47, s78, 64
	v_add_f32_e32 v58, v26, v3
	v_and_b32_e32 v58, s78, v58
	v_or_b32_e32 v58, 0x41, v58
	v_add_f32_e32 v59, v26, v4
	v_and_b32_e32 v59, s78, v59
	v_or_b32_e32 v59, 0x42, v59
	v_add_f32_e32 v60, v27, v3
	v_and_b32_e32 v60, s78, v60
	v_or_b32_e32 v60, 0x51, v60
	v_add_f32_e32 v61, v28, v3
	v_and_b32_e32 v61, s78, v61
	v_or_b32_e32 v61, 0x61, v61
	v_add_f32_e32 v154, v29, v3
	v_and_b32_e32 v154, s78, v154
	v_or_b32_e32 v154, 0x71, v154
	v_max_f32_e32 v205, v58, v154
	v_min_f32_e32 v154, v58, v154
	v_max_f32_e32 v58, v59, v61
	v_min_f32_e32 v61, v59, v61
	v_max_f32_e32 v59, v47, v58
	v_min_f32_e32 v58, v47, v58
	v_max_f32_e32 v47, v205, v60
	v_min_f32_e32 v60, v205, v60
	v_max_f32_e32 v205, v59, v47
	v_min_f32_e32 v47, v59, v47
	v_max_f32_e32 v59, v58, v60
	v_min_f32_e32 v60, v58, v60
	v_max_f32_e32 v58, v61, v154
	v_min_f32_e32 v154, v61, v154
	v_add_f32_e32 v61, v33, v2
	v_and_or_b32 v61, v61, s78, 48
	v_add_f32_e32 v206, v33, v3
	v_and_or_b32 v206, v206, s78, 49
	v_add_f32_e32 v207, v33, v4
	v_and_or_b32 v207, v207, s78, 50
	v_add_f32_e32 v227, v33, v5
	v_and_or_b32 v227, v227, s78, 51
	v_max_f32_e32 v228, v207, v154
	v_min_f32_e32 v154, v207, v154
	v_max_f32_e32 v207, v227, v58
	v_min_f32_e32 v58, v227, v58
	v_max_f32_e32 v227, v61, v60
	v_min_f32_e32 v60, v61, v60
	v_max_f32_e32 v61, v206, v59
	v_min_f32_e32 v59, v206, v59
	v_max_f32_e32 v206, v228, v47
	v_min_f32_e32 v47, v228, v47
	v_max_f32_e32 v228, v207, v205
	v_min_f32_e32 v205, v207, v205
	v_max_f32_e32 v207, v227, v206
	v_min_f32_e32 v206, v227, v206
	v_max_f32_e32 v227, v61, v228
	v_min_f32_e32 v228, v61, v228
	v_max_f32_e32 v61, v60, v47
	v_min_f32_e32 v47, v60, v47
	v_max_f32_e32 v60, v59, v205
	v_min_f32_e32 v205, v59, v205
	v_max_f32_e32 v59, v207, v227
	v_min_f32_e32 v227, v207, v227
	v_max_f32_e32 v207, v206, v228
	v_min_f32_e32 v228, v206, v228
	v_max_f32_e32 v206, v61, v60
	v_min_f32_e32 v60, v61, v60
	v_max_f32_e32 v61, v47, v205
	v_min_f32_e32 v205, v47, v205
	v_max_f32_e32 v47, v154, v58
	v_min_f32_e32 v58, v154, v58
	v_add_f32_e32 v154, v31, v2
	v_and_or_b32 v154, v154, s78, 16
	v_add_f32_e32 v229, v31, v3
	v_and_or_b32 v229, v229, s78, 17
	v_add_f32_e32 v230, v31, v4
	v_and_or_b32 v230, v230, s78, 18
	v_add_f32_e32 v231, v31, v5
	v_and_or_b32 v231, v231, s78, 19
	v_add_f32_e32 v232, v31, v14
	v_and_or_b32 v232, v232, s78, 20
	v_add_f32_e32 v22, v31, v15
	v_and_or_b32 v22, v22, s78, 21
	v_add_f32_e32 v23, v31, v16
	v_and_or_b32 v23, v23, s78, 22
	v_add_f32_e32 v18, v31, v17
	v_and_or_b32 v18, v18, s78, 23
	v_max_f32_e32 v23, v23, v58
	v_max_f32_e32 v18, v18, v47
	v_max_f32_e32 v47, v154, v205
	v_min_f32_e32 v205, v154, v205
	v_max_f32_e32 v58, v229, v61
	v_min_f32_e32 v61, v229, v61
	v_max_f32_e32 v154, v230, v60
	v_min_f32_e32 v60, v230, v60
	v_max_f32_e32 v229, v231, v206
	v_min_f32_e32 v206, v231, v206
	v_max_f32_e32 v230, v232, v228
	v_min_f32_e32 v228, v232, v228
	v_max_f32_e32 v231, v22, v207
	v_min_f32_e32 v207, v22, v207
	v_max_f32_e32 v232, v23, v227
	v_min_f32_e32 v227, v23, v227
	v_max_f32_e32 v22, v18, v59
	v_min_f32_e32 v59, v18, v59
	v_max_f32_e32 v23, v47, v230
	v_min_f32_e32 v230, v47, v230
	v_max_f32_e32 v47, v58, v231
	v_min_f32_e32 v231, v58, v231
	v_max_f32_e32 v58, v154, v232
	v_min_f32_e32 v232, v154, v232
	v_max_f32_e32 v154, v229, v22
	v_min_f32_e32 v22, v229, v22
	v_max_f32_e32 v229, v205, v228
	v_min_f32_e32 v228, v205, v228
	v_max_f32_e32 v205, v61, v207
	v_min_f32_e32 v207, v61, v207
	v_max_f32_e32 v61, v60, v227
	v_min_f32_e32 v227, v60, v227
	v_max_f32_e32 v60, v206, v59
	v_min_f32_e32 v59, v206, v59
	v_max_f32_e32 v206, v23, v58
	v_min_f32_e32 v58, v23, v58
	v_max_f32_e32 v23, v47, v154
	v_min_f32_e32 v154, v47, v154
	v_max_f32_e32 v47, v230, v232
	v_min_f32_e32 v232, v230, v232
	v_max_f32_e32 v230, v231, v22
	v_min_f32_e32 v22, v231, v22
	v_max_f32_e32 v231, v229, v61
	v_min_f32_e32 v61, v229, v61
	v_max_f32_e32 v229, v205, v60
	v_min_f32_e32 v60, v205, v60
	v_max_f32_e32 v205, v228, v227
	v_min_f32_e32 v227, v228, v227
	v_max_f32_e32 v228, v207, v59
	v_min_f32_e32 v59, v207, v59
	v_max_f32_e32 v207, v206, v23
	v_min_f32_e32 v23, v206, v23
	v_max_f32_e32 v206, v58, v154
	v_min_f32_e32 v154, v58, v154
	v_max_f32_e32 v58, v47, v230
	v_min_f32_e32 v230, v47, v230
	v_max_f32_e32 v47, v232, v22
	v_min_f32_e32 v22, v232, v22
	v_max_f32_e32 v232, v231, v229
	v_min_f32_e32 v229, v231, v229
	v_max_f32_e32 v231, v61, v60
	v_min_f32_e32 v60, v61, v60
	v_max_f32_e32 v61, v205, v228
	v_min_f32_e32 v228, v205, v228
	v_max_f32_e32 v205, v227, v59
	v_min_f32_e32 v59, v227, v59
	v_max_f32_e32 v48, v48, v59
	v_max_f32_e32 v54, v54, v205
	v_max_f32_e32 v50, v50, v228
	v_max_f32_e32 v42, v42, v61
	v_max_f32_e32 v35, v35, v60
	v_max_f32_e32 v44, v44, v231
	v_max_f32_e32 v57, v57, v229
	v_max_f32_e32 v55, v55, v232
	v_max_f32_e32 v56, v56, v22
	v_max_f32_e32 v43, v43, v47
	v_max_f32_e32 v45, v45, v230
	v_max_f32_e32 v51, v51, v58
	v_max_f32_e32 v52, v52, v154
	v_max_f32_e32 v49, v49, v206
	v_max_f32_e32 v53, v53, v23
	v_max_f32_e32 v46, v46, v207
	v_max_f32_e32 v47, v48, v56
	v_min_f32_e32 v56, v48, v56
	v_max_f32_e32 v48, v54, v43
	v_min_f32_e32 v43, v54, v43
	v_max_f32_e32 v54, v50, v45
	v_min_f32_e32 v45, v50, v45
	v_max_f32_e32 v50, v42, v51
	v_min_f32_e32 v51, v42, v51
	v_max_f32_e32 v42, v35, v52
	v_min_f32_e32 v52, v35, v52
	v_max_f32_e32 v35, v44, v49
	v_min_f32_e32 v49, v44, v49
	v_max_f32_e32 v44, v57, v53
	v_min_f32_e32 v53, v57, v53
	v_max_f32_e32 v57, v55, v46
	v_min_f32_e32 v46, v55, v46
	v_max_f32_e32 v55, v47, v42
	v_min_f32_e32 v42, v47, v42
	v_max_f32_e32 v47, v48, v35
	v_min_f32_e32 v35, v48, v35
	v_max_f32_e32 v48, v54, v44
	v_min_f32_e32 v44, v54, v44
	v_max_f32_e32 v54, v50, v57
	v_min_f32_e32 v57, v50, v57
	v_max_f32_e32 v50, v56, v52
	v_min_f32_e32 v52, v56, v52
	v_max_f32_e32 v56, v43, v49
	v_min_f32_e32 v49, v43, v49
	v_max_f32_e32 v43, v45, v53
	v_min_f32_e32 v53, v45, v53
	v_max_f32_e32 v45, v51, v46
	v_min_f32_e32 v46, v51, v46
	v_max_f32_e32 v51, v55, v48
	v_min_f32_e32 v48, v55, v48
	v_max_f32_e32 v55, v47, v54
	v_min_f32_e32 v54, v47, v54
	v_max_f32_e32 v47, v42, v44
	v_min_f32_e32 v44, v42, v44
	v_max_f32_e32 v42, v35, v57
	v_min_f32_e32 v57, v35, v57
	v_max_f32_e32 v35, v50, v43
	v_min_f32_e32 v43, v50, v43
	v_max_f32_e32 v50, v56, v45
	v_min_f32_e32 v45, v56, v45
	v_max_f32_e32 v56, v52, v53
	v_min_f32_e32 v53, v52, v53
	v_max_f32_e32 v52, v49, v46
	v_min_f32_e32 v46, v49, v46
	v_max_f32_e32 v49, v51, v55
	v_min_f32_e32 v55, v51, v55
	v_max_f32_e32 v51, v48, v54
	v_min_f32_e32 v54, v48, v54
	v_max_f32_e32 v48, v47, v42
	v_min_f32_e32 v42, v47, v42
	v_max_f32_e32 v47, v44, v57
	v_min_f32_e32 v57, v44, v57
	v_max_f32_e32 v44, v35, v50
	v_min_f32_e32 v50, v35, v50
	v_max_f32_e32 v35, v43, v45
	v_min_f32_e32 v45, v43, v45
	v_max_f32_e32 v43, v56, v52
	v_min_f32_e32 v52, v56, v52
	v_max_f32_e32 v56, v53, v46
	v_min_f32_e32 v46, v53, v46
	v_add_f32_e32 v53, v30, v2
	v_and_or_b32 v53, v53, s78, 0
	v_add_f32_e32 v58, v30, v3
	v_and_or_b32 v58, v58, s78, 1
	v_add_f32_e32 v59, v30, v4
	v_and_or_b32 v59, v59, s78, 2
	v_add_f32_e32 v60, v30, v5
	v_and_or_b32 v60, v60, s78, 3
	v_add_f32_e32 v61, v30, v14
	v_and_or_b32 v61, v61, s78, 4
	v_add_f32_e32 v154, v30, v15
	v_and_or_b32 v154, v154, s78, 5
	v_add_f32_e32 v205, v30, v16
	v_and_or_b32 v205, v205, s78, 6
	v_add_f32_e32 v206, v30, v17
	v_and_or_b32 v206, v206, s78, 7
	v_add_f32_e32 v207, v30, v10
	v_and_or_b32 v207, v207, s78, 8
	v_add_f32_e32 v227, v30, v11
	v_and_or_b32 v227, v227, s78, 9
	v_add_f32_e32 v228, v30, v12
	v_and_or_b32 v228, v228, s78, 10
	v_add_f32_e32 v229, v30, v13
	v_and_or_b32 v229, v229, s78, 11
	v_add_f32_e32 v230, v30, v6
	v_and_or_b32 v230, v230, s78, 12
	v_add_f32_e32 v231, v30, v7
	v_and_or_b32 v231, v231, s78, 13
	v_add_f32_e32 v232, v30, v8
	v_and_or_b32 v232, v232, s78, 14
	v_add_f32_e32 v22, v30, v9
	v_and_or_b32 v22, v22, s78, 15
	v_max_f32_e32 v53, v53, v46
	v_max_f32_e32 v58, v58, v56
	v_max_f32_e32 v59, v59, v52
	v_max_f32_e32 v60, v60, v43
	v_max_f32_e32 v61, v61, v45
	v_max_f32_e32 v154, v154, v35
	v_max_f32_e32 v205, v205, v50
	v_max_f32_e32 v206, v206, v44
	v_max_f32_e32 v207, v207, v57
	v_max_f32_e32 v227, v227, v47
	v_max_f32_e32 v228, v228, v42
	v_max_f32_e32 v229, v229, v48
	v_max_f32_e32 v230, v230, v54
	v_max_f32_e32 v231, v231, v51
	v_max_f32_e32 v232, v232, v55
	v_max_f32_e32 v22, v22, v49
	v_max_f32_e32 v35, v53, v207
	v_min_f32_e32 v207, v53, v207
	v_max_f32_e32 v42, v58, v227
	v_min_f32_e32 v227, v58, v227
	v_max_f32_e32 v43, v59, v228
	v_min_f32_e32 v228, v59, v228
	v_max_f32_e32 v44, v60, v229
	v_min_f32_e32 v229, v60, v229
	v_max_f32_e32 v45, v61, v230
	v_min_f32_e32 v230, v61, v230
	v_max_f32_e32 v46, v154, v231
	v_min_f32_e32 v231, v154, v231
	v_max_f32_e32 v47, v205, v232
	v_min_f32_e32 v232, v205, v232
	v_max_f32_e32 v48, v206, v22
	v_min_f32_e32 v22, v206, v22
	v_max_f32_e32 v49, v35, v45
	v_min_f32_e32 v45, v35, v45
	v_max_f32_e32 v35, v42, v46
	v_min_f32_e32 v46, v42, v46
	v_max_f32_e32 v42, v43, v47
	v_min_f32_e32 v47, v43, v47
	v_max_f32_e32 v43, v44, v48
	v_min_f32_e32 v48, v44, v48
	v_max_f32_e32 v44, v207, v230
	v_min_f32_e32 v230, v207, v230
	v_max_f32_e32 v50, v227, v231
	v_min_f32_e32 v231, v227, v231
	v_max_f32_e32 v51, v228, v232
	v_min_f32_e32 v232, v228, v232
	v_max_f32_e32 v52, v229, v22
	v_min_f32_e32 v22, v229, v22
	v_max_f32_e32 v53, v49, v42
	v_min_f32_e32 v42, v49, v42
	v_max_f32_e32 v49, v35, v43
	v_min_f32_e32 v43, v35, v43
	v_max_f32_e32 v35, v45, v47
	v_min_f32_e32 v47, v45, v47
	v_max_f32_e32 v45, v46, v48
	v_min_f32_e32 v48, v46, v48
	v_max_f32_e32 v46, v44, v51
	v_min_f32_e32 v51, v44, v51
	v_max_f32_e32 v44, v50, v52
	v_min_f32_e32 v52, v50, v52
	v_max_f32_e32 v50, v230, v232
	v_min_f32_e32 v232, v230, v232
	v_max_f32_e32 v54, v231, v22
	v_min_f32_e32 v22, v231, v22
	v_max_f32_e32 v41, v53, v49
	v_min_f32_e32 v40, v53, v49
	v_max_f32_e32 v39, v42, v43
	v_min_f32_e32 v38, v42, v43
	v_max_f32_e32 v37, v35, v45
	v_min_f32_e32 v33, v35, v45
	v_max_f32_e32 v32, v47, v48
	v_min_f32_e32 v31, v47, v48
	v_max_f32_e32 v30, v46, v44
	v_min_f32_e32 v29, v46, v44
	v_max_f32_e32 v28, v51, v52
	v_min_f32_e32 v27, v51, v52
	v_max_f32_e32 v26, v50, v54
	v_min_f32_e32 v25, v50, v54
	v_max_f32_e32 v24, v232, v22
	v_min_f32_e32 v19, v232, v22
	v_and_b32_e32 v17, 0xffffff00, v41
	v_sub_f32_e32 v2, v17, v17
	v_mul_f32_e32 v6, 0x3fb8aa3b, v2
	v_fma_f32 v7, v2, s79, -v6
	v_rndne_f32_e32 v22, v6
	v_fmac_f32_e32 v7, 0x32a5705f, v2
	v_sub_f32_e32 v6, v6, v22
	v_add_f32_e32 v6, v6, v7
	v_exp_f32_e32 v6, v6
	v_cvt_i32_f32_e32 v7, v22
	v_and_b32_e32 v3, 0xffffff00, v40
	v_cmp_ngt_f32_e32 vcc, s80, v2
	v_sub_f32_e32 v3, v3, v17
	v_ldexp_f32 v6, v6, v7
	v_cndmask_b32_e32 v6, 0, v6, vcc
	v_and_b32_e32 v4, 0xffffff00, v39
	v_sub_f32_e32 v4, v4, v17
	v_mov_b32_e32 v2, v6
	v_mul_f32_e32 v6, 0x3fb8aa3b, v3
	v_fma_f32 v7, v3, s79, -v6
	v_rndne_f32_e32 v22, v6
	v_fmac_f32_e32 v7, 0x32a5705f, v3
	v_sub_f32_e32 v6, v6, v22
	v_add_f32_e32 v6, v6, v7
	v_exp_f32_e32 v6, v6
	v_cvt_i32_f32_e32 v7, v22
	v_cmp_ngt_f32_e32 vcc, s80, v3
	v_and_b32_e32 v5, 0xffffff00, v38
	v_sub_f32_e32 v5, v5, v17
	v_ldexp_f32 v6, v6, v7
	v_cndmask_b32_e32 v6, 0, v6, vcc
	v_and_b32_e32 v8, 0xffffff00, v37
	v_and_b32_e32 v9, 0xffffff00, v33
	v_mov_b32_e32 v3, v6
	v_mul_f32_e32 v6, 0x3fb8aa3b, v4
	v_fma_f32 v22, v4, s79, -v6
	v_rndne_f32_e32 v23, v6
	v_fmac_f32_e32 v22, 0x32a5705f, v4
	v_sub_f32_e32 v6, v6, v23
	v_add_f32_e32 v6, v6, v22
	v_exp_f32_e32 v6, v6
	v_cvt_i32_f32_e32 v22, v23
	v_cmp_ngt_f32_e32 vcc, s80, v4
	v_add_f32_e32 v7, v2, v3
	v_and_b32_e32 v10, 0xffffff00, v32
	v_ldexp_f32 v6, v6, v22
	v_cndmask_b32_e32 v6, 0, v6, vcc
	v_and_b32_e32 v11, 0xffffff00, v31
	v_and_b32_e32 v12, 0xffffff00, v30
	v_add_f32_e32 v4, v7, v6
	v_mul_f32_e32 v7, 0x3fb8aa3b, v5
	v_fma_f32 v22, v5, s79, -v7
	v_rndne_f32_e32 v23, v7
	v_fmac_f32_e32 v22, 0x32a5705f, v5
	v_sub_f32_e32 v7, v7, v23
	v_add_f32_e32 v7, v7, v22
	v_exp_f32_e32 v7, v7
	v_cvt_i32_f32_e32 v22, v23
	v_cmp_ngt_f32_e32 vcc, s80, v5
	v_and_b32_e32 v14, 0xffffff00, v29
	v_and_b32_e32 v15, 0xffffff00, v28
	v_ldexp_f32 v7, v7, v22
	v_cndmask_b32_e32 v7, 0, v7, vcc
	v_and_b32_e32 v20, 0xffffff00, v27
	v_and_b32_e32 v21, 0xffffff00, v26
	v_add_f32_e32 v5, v4, v7
	v_sub_f32_e32 v4, v8, v17
	v_mul_f32_e32 v8, 0x3fb8aa3b, v4
	v_fma_f32 v22, v4, s79, -v8
	v_rndne_f32_e32 v23, v8
	v_fmac_f32_e32 v22, 0x32a5705f, v4
	v_sub_f32_e32 v8, v8, v23
	v_add_f32_e32 v8, v8, v22
	v_exp_f32_e32 v8, v8
	v_cvt_i32_f32_e32 v22, v23
	v_cmp_ngt_f32_e32 vcc, s80, v4
	v_and_b32_e32 v13, 0xffffff00, v25
	v_sub_f32_e32 v13, v13, v17
	v_ldexp_f32 v8, v8, v22
	v_cndmask_b32_e32 v8, 0, v8, vcc
	v_and_b32_e32 v16, 0xffffff00, v24
	v_sub_f32_e32 v16, v16, v17
	v_mov_b32_e32 v4, v8
	v_add_f32_e32 v8, v5, v4
	v_sub_f32_e32 v5, v9, v17
	v_mul_f32_e32 v9, 0x3fb8aa3b, v5
	v_fma_f32 v22, v5, s79, -v9
	v_rndne_f32_e32 v23, v9
	v_fmac_f32_e32 v22, 0x32a5705f, v5
	v_sub_f32_e32 v9, v9, v23
	v_add_f32_e32 v9, v9, v22
	v_exp_f32_e32 v9, v9
	v_cvt_i32_f32_e32 v22, v23
	v_cmp_ngt_f32_e32 vcc, s80, v5
	v_and_b32_e32 v18, 0xffffff00, v19
	s_mov_b32 s10, s42
	v_ldexp_f32 v9, v9, v22
	v_cndmask_b32_e32 v9, 0, v9, vcc
	v_or_b32_e32 v34, s10, v34
	v_lshrrev_b32_e32 v42, 2, v39
	v_mov_b32_e32 v5, v9
	v_sub_f32_e32 v9, v10, v17
	v_mul_f32_e32 v10, 0x3fb8aa3b, v9
	v_fma_f32 v22, v9, s79, -v10
	v_rndne_f32_e32 v23, v10
	v_fmac_f32_e32 v22, 0x32a5705f, v9
	v_sub_f32_e32 v10, v10, v23
	v_add_f32_e32 v10, v10, v22
	v_exp_f32_e32 v10, v10
	v_cvt_i32_f32_e32 v22, v23
	v_cmp_ngt_f32_e32 vcc, s80, v9
	v_add_f32_e32 v8, v8, v5
	v_and_b32_e32 v39, 15, v39
	v_ldexp_f32 v10, v10, v22
	v_cndmask_b32_e32 v10, 0, v10, vcc
	v_sub_f32_e32 v9, v11, v17
	v_mul_f32_e32 v11, 0x3fb8aa3b, v9
	v_fma_f32 v22, v9, s79, -v11
	v_rndne_f32_e32 v23, v11
	v_fmac_f32_e32 v22, 0x32a5705f, v9
	v_sub_f32_e32 v11, v11, v23
	v_add_f32_e32 v11, v11, v22
	v_exp_f32_e32 v11, v11
	v_cvt_i32_f32_e32 v22, v23
	v_cmp_ngt_f32_e32 vcc, s80, v9
	v_add_f32_e32 v8, v8, v10
	v_ldexp_f32 v11, v11, v22
	v_cndmask_b32_e32 v11, 0, v11, vcc
	v_lshl_add_u32 v39, v39, 2, v36
	ds_read_b32 v43, v39 offset:64
	v_add_f32_e32 v9, v8, v11
	v_sub_f32_e32 v8, v12, v17
	v_mul_f32_e32 v12, 0x3fb8aa3b, v8
	v_fma_f32 v22, v8, s79, -v12
	v_rndne_f32_e32 v23, v12
	v_fmac_f32_e32 v22, 0x32a5705f, v8
	v_sub_f32_e32 v12, v12, v23
	v_add_f32_e32 v12, v12, v22
	v_exp_f32_e32 v12, v12
	v_cvt_i32_f32_e32 v22, v23
	v_cmp_ngt_f32_e32 vcc, s80, v8
	v_lshrrev_b32_e32 v39, 2, v38
	v_and_b32_e32 v42, 60, v42
	v_ldexp_f32 v12, v12, v22
	v_cndmask_b32_e32 v12, 0, v12, vcc
	v_and_b32_e32 v39, 60, v39
	v_add_u32_e32 v42, v36, v42
	v_mov_b32_e32 v8, v12
	v_add_f32_e32 v12, v9, v8
	v_sub_f32_e32 v9, v14, v17
	v_mul_f32_e32 v14, 0x3fb8aa3b, v9
	v_fma_f32 v22, v9, s79, -v14
	v_rndne_f32_e32 v23, v14
	v_fmac_f32_e32 v22, 0x32a5705f, v9
	v_sub_f32_e32 v14, v14, v23
	v_add_f32_e32 v14, v14, v22
	v_exp_f32_e32 v14, v14
	v_cvt_i32_f32_e32 v22, v23
	v_cmp_ngt_f32_e32 vcc, s80, v9
	v_add_u32_e32 v39, v36, v39
	v_and_b32_e32 v38, 15, v38
	v_ldexp_f32 v14, v14, v22
	v_cndmask_b32_e32 v14, 0, v14, vcc
	ds_read_b32 v42, v42
	ds_read_b32 v44, v39
	v_mov_b32_e32 v9, v14
	v_sub_f32_e32 v14, v15, v17
	v_mul_f32_e32 v15, 0x3fb8aa3b, v14
	v_fma_f32 v22, v14, s79, -v15
	v_rndne_f32_e32 v23, v15
	v_fmac_f32_e32 v22, 0x32a5705f, v14
	v_sub_f32_e32 v15, v15, v23
	v_add_f32_e32 v15, v15, v22
	v_exp_f32_e32 v15, v15
	v_cvt_i32_f32_e32 v22, v23
	v_cmp_ngt_f32_e32 vcc, s80, v14
	v_add_f32_e32 v12, v12, v9
	v_lshl_add_u32 v38, v38, 2, v36
	v_ldexp_f32 v15, v15, v22
	v_cndmask_b32_e32 v15, 0, v15, vcc
	ds_read_b32 v45, v38 offset:64
	s_nop 0
	v_mov_b32_e32 v14, v15
	v_sub_f32_e32 v15, v20, v17
	v_mul_f32_e32 v20, 0x3fb8aa3b, v15
	v_fma_f32 v22, v15, s79, -v20
	v_rndne_f32_e32 v23, v20
	v_fmac_f32_e32 v22, 0x32a5705f, v15
	v_sub_f32_e32 v20, v20, v23
	v_add_f32_e32 v20, v20, v22
	v_exp_f32_e32 v20, v20
	v_cvt_i32_f32_e32 v22, v23
	v_cmp_ngt_f32_e32 vcc, s80, v15
	v_add_f32_e32 v12, v12, v14
	v_ldexp_f32 v20, v20, v22
	v_cndmask_b32_e32 v20, 0, v20, vcc
	s_nop 1
	v_mov_b32_e32 v15, v20
	v_add_f32_e32 v20, v12, v15
	v_sub_f32_e32 v12, v21, v17
	v_mul_f32_e32 v21, 0x3fb8aa3b, v12
	v_fma_f32 v22, v12, s79, -v21
	v_rndne_f32_e32 v23, v21
	v_fmac_f32_e32 v22, 0x32a5705f, v12
	v_sub_f32_e32 v21, v21, v23
	v_add_f32_e32 v21, v21, v22
	v_exp_f32_e32 v21, v21
	v_cvt_i32_f32_e32 v22, v23
	v_cmp_ngt_f32_e32 vcc, s80, v12
	v_sub_f32_e32 v17, v18, v17
	v_mul_f32_e32 v18, 0x3fb8aa3b, v17
	v_ldexp_f32 v21, v21, v22
	v_cndmask_b32_e32 v21, 0, v21, vcc
	s_nop 1
	v_mov_b32_e32 v12, v21
	v_mul_f32_e32 v21, 0x3fb8aa3b, v13
	v_fma_f32 v22, v13, s79, -v21
	v_rndne_f32_e32 v23, v21
	v_fmac_f32_e32 v22, 0x32a5705f, v13
	v_sub_f32_e32 v21, v21, v23
	v_add_f32_e32 v21, v21, v22
	v_exp_f32_e32 v21, v21
	v_cvt_i32_f32_e32 v22, v23
	v_cmp_ngt_f32_e32 vcc, s80, v13
	v_add_f32_e32 v20, v20, v12
	v_ldexp_f32 v21, v21, v22
	v_cndmask_b32_e32 v21, 0, v21, vcc
	s_nop 1
	v_mov_b32_e32 v13, v21
	v_mul_f32_e32 v21, 0x3fb8aa3b, v16
	v_fma_f32 v22, v16, s79, -v21
	v_rndne_f32_e32 v23, v21
	v_fmac_f32_e32 v22, 0x32a5705f, v16
	v_sub_f32_e32 v21, v21, v23
	v_add_f32_e32 v21, v21, v22
	v_exp_f32_e32 v21, v21
	v_cvt_i32_f32_e32 v22, v23
	v_cmp_ngt_f32_e32 vcc, s80, v16
	v_add_f32_e32 v20, v20, v13
	v_ldexp_f32 v21, v21, v22
	v_cndmask_b32_e32 v21, 0, v21, vcc
	v_rndne_f32_e32 v22, v18
	s_nop 0
	v_mov_b32_e32 v16, v21
	v_fma_f32 v21, v17, s79, -v18
	v_fmac_f32_e32 v21, 0x32a5705f, v17
	v_sub_f32_e32 v18, v18, v22
	v_add_f32_e32 v18, v18, v21
	v_exp_f32_e32 v18, v18
	v_cvt_i32_f32_e32 v21, v22
	v_cmp_ngt_f32_e32 vcc, s80, v17
	v_add_f32_e32 v20, v20, v16
	v_ldexp_f32 v18, v18, v21
	v_cndmask_b32_e32 v18, 0, v18, vcc
	s_nop 1
	v_mov_b32_e32 v17, v18
	v_add_f32_e32 v18, v20, v17
	v_div_scale_f32 v20, s[10:11], v18, v18, 1.0
	v_rcp_f32_e32 v21, v20
	s_nop 0
	v_fma_f32 v22, -v20, v21, 1.0
	v_fmac_f32_e32 v21, v22, v21
	v_div_scale_f32 v22, vcc, 1.0, v18, 1.0
	v_mul_f32_e32 v23, v22, v21
	v_fma_f32 v35, -v20, v23, v22
	v_fmac_f32_e32 v23, v35, v21
	v_fma_f32 v20, -v20, v23, v22
	v_div_fmas_f32 v20, v20, v21, v23
	v_ashrrev_i32_e32 v35, 31, v34
	v_div_fixup_f32 v18, v20, v18, 1.0
	v_lshlrev_b64 v[20:21], 9, v[34:35]
	v_lshrrev_b32_e32 v34, 2, v41
	v_and_b32_e32 v35, 15, v41
	v_lshrrev_b32_e32 v41, 2, v40
	v_and_b32_e32 v41, 60, v41
	v_add_u32_e32 v41, v36, v41
	v_and_b32_e32 v34, 60, v34
	ds_read_b32 v41, v41
	v_add_u32_e32 v34, v36, v34
	v_and_b32_e32 v40, 15, v40
	ds_read_b32 v34, v34
	v_lshl_add_u32 v35, v35, 2, v36
	v_lshl_add_u32 v40, v40, 2, v36
	ds_read_b32 v35, v35 offset:64
	ds_read_b32 v40, v40 offset:64
	s_waitcnt lgkmcnt(3)
	v_lshlrev_b32_e32 v39, 7, v41
	s_waitcnt lgkmcnt(2)
	v_lshlrev_b32_e32 v34, 7, v34
	v_and_b32_e32 v39, 0x3f80, v39
	s_waitcnt lgkmcnt(1)
	v_and_b32_e32 v35, 0x7f, v35
	s_waitcnt lgkmcnt(0)
	v_and_b32_e32 v38, 0x7f, v40
	v_and_b32_e32 v34, 0x3f80, v34
	v_lshlrev_b32_e32 v40, 7, v44
	v_lshlrev_b32_e32 v41, 7, v42
	v_or_b32_e32 v39, v39, v38
	v_or_b32_e32 v38, v34, v35
	v_and_b32_e32 v34, 0x7f, v45
	v_and_b32_e32 v35, 0x7f, v43
	v_and_b32_e32 v40, 0x3f80, v40
	v_and_b32_e32 v42, 0x3f80, v41
	v_lshl_add_u64 v[22:23], s[0:1], 0, v[20:21]
	v_or_b32_e32 v41, v40, v34
	v_or_b32_e32 v40, v42, v35
	global_store_dwordx4 v[22:23], v[38:41], off
	v_lshl_add_u64 v[20:21], s[14:15], 0, v[20:21]
	v_pk_mul_f32 v[4:5], v[4:5], v[18:19] op_sel_hi:[1,0]
	v_pk_mul_f32 v[40:41], v[6:7], v[18:19] op_sel_hi:[1,0]
	v_pk_mul_f32 v[38:39], v[2:3], v[18:19] op_sel_hi:[1,0]
	v_lshrrev_b32_e32 v2, 2, v37
	v_lshrrev_b32_e32 v6, 2, v33
	v_and_b32_e32 v7, 15, v33
	v_lshrrev_b32_e32 v33, 2, v32
	v_and_b32_e32 v32, 15, v32
	v_and_b32_e32 v2, 60, v2
	v_and_b32_e32 v3, 15, v37
	v_and_b32_e32 v6, 60, v6
	v_lshl_add_u32 v32, v32, 2, v36
	v_add_u32_e32 v2, v36, v2
	v_lshl_add_u32 v3, v3, 2, v36
	v_add_u32_e32 v6, v36, v6
	ds_read_b32 v35, v32 offset:64
	v_lshrrev_b32_e32 v32, 2, v31
	ds_read_b32 v2, v2
	ds_read_b32 v3, v3 offset:64
	ds_read_b32 v6, v6
	v_lshl_add_u32 v7, v7, 2, v36
	v_and_b32_e32 v33, 60, v33
	v_and_b32_e32 v32, 60, v32
	ds_read_b32 v7, v7 offset:64
	v_add_u32_e32 v33, v36, v33
	v_add_u32_e32 v32, v36, v32
	v_and_b32_e32 v31, 15, v31
	ds_read_b32 v34, v33
	ds_read_b32 v37, v32
	v_lshl_add_u32 v31, v31, 2, v36
	ds_read_b32 v31, v31 offset:64
	s_waitcnt lgkmcnt(4)
	v_lshlrev_b32_e32 v6, 7, v6
	s_waitcnt lgkmcnt(3)
	v_and_b32_e32 v7, 0x7f, v7
	v_lshlrev_b32_e32 v2, 7, v2
	v_and_b32_e32 v6, 0x3f80, v6
	v_and_b32_e32 v3, 0x7f, v3
	v_and_b32_e32 v2, 0x3f80, v2
	v_or_b32_e32 v33, v6, v7
	s_waitcnt lgkmcnt(1)
	v_lshlrev_b32_e32 v6, 7, v37
	v_lshlrev_b32_e32 v7, 7, v34
	v_or_b32_e32 v32, v2, v3
	s_waitcnt lgkmcnt(0)
	v_and_b32_e32 v2, 0x7f, v31
	v_and_b32_e32 v3, 0x7f, v35
	v_and_b32_e32 v6, 0x3f80, v6
	v_and_b32_e32 v7, 0x3f80, v7
	v_or_b32_e32 v35, v6, v2
	v_or_b32_e32 v34, v7, v3
	v_pk_mul_f32 v[6:7], v[10:11], v[18:19] op_sel_hi:[1,0]
	global_store_dwordx4 v[20:21], v[4:7], off offset:16
	v_lshrrev_b32_e32 v2, 2, v30
	v_and_b32_e32 v2, 60, v2
	v_lshrrev_b32_e32 v4, 2, v29
	v_and_b32_e32 v3, 15, v30
	v_and_b32_e32 v4, 60, v4
	v_add_u32_e32 v2, v36, v2
	v_lshl_add_u32 v3, v3, 2, v36
	v_add_u32_e32 v4, v36, v4
	v_and_b32_e32 v5, 15, v29
	v_lshrrev_b32_e32 v6, 2, v28
	v_lshrrev_b32_e32 v10, 2, v27
	ds_read_b32 v2, v2
	ds_read_b32 v3, v3 offset:64
	ds_read_b32 v4, v4
	v_lshl_add_u32 v5, v5, 2, v36
	v_and_b32_e32 v6, 60, v6
	v_and_b32_e32 v7, 15, v28
	v_and_b32_e32 v10, 60, v10
	ds_read_b32 v5, v5 offset:64
	v_add_u32_e32 v6, v36, v6
	v_lshl_add_u32 v7, v7, 2, v36
	v_add_u32_e32 v10, v36, v10
	v_and_b32_e32 v11, 15, v27
	ds_read_b32 v6, v6
	ds_read_b32 v7, v7 offset:64
	ds_read_b32 v10, v10
	v_lshl_add_u32 v11, v11, 2, v36
	ds_read_b32 v11, v11 offset:64
	s_waitcnt lgkmcnt(6)
	v_and_b32_e32 v27, 0x7f, v3
	s_waitcnt lgkmcnt(5)
	v_lshlrev_b32_e32 v3, 7, v4
	s_waitcnt lgkmcnt(4)
	v_and_b32_e32 v5, 0x7f, v5
	v_and_b32_e32 v3, 0x3f80, v3
	v_lshlrev_b32_e32 v2, 7, v2
	v_or_b32_e32 v3, v3, v5
	s_waitcnt lgkmcnt(1)
	v_lshlrev_b32_e32 v5, 7, v10
	v_lshlrev_b32_e32 v6, 7, v6
	v_and_b32_e32 v2, 0x3f80, v2
	s_waitcnt lgkmcnt(0)
	v_and_b32_e32 v4, 0x7f, v11
	v_and_b32_e32 v7, 0x7f, v7
	v_and_b32_e32 v5, 0x3f80, v5
	v_and_b32_e32 v6, 0x3f80, v6
	v_or_b32_e32 v2, v2, v27
	v_or_b32_e32 v5, v5, v4
	v_or_b32_e32 v4, v6, v7
	global_store_dwordx4 v[22:23], v[2:5], off offset:32
	v_lshrrev_b32_e32 v6, 2, v24
	v_and_b32_e32 v6, 60, v6
	v_pk_mul_f32 v[4:5], v[14:15], v[18:19] op_sel_hi:[1,0]
	v_pk_mul_f32 v[2:3], v[8:9], v[18:19] op_sel_hi:[1,0]
	global_store_dwordx4 v[20:21], v[2:5], off offset:32
	v_lshrrev_b32_e32 v8, 2, v19
	v_and_b32_e32 v7, 15, v24
	v_lshrrev_b32_e32 v2, 2, v26
	v_lshrrev_b32_e32 v4, 2, v25
	v_and_b32_e32 v2, 60, v2
	v_and_b32_e32 v3, 15, v26
	v_and_b32_e32 v4, 60, v4
	v_add_u32_e32 v2, v36, v2
	v_lshl_add_u32 v3, v3, 2, v36
	v_add_u32_e32 v4, v36, v4
	v_and_b32_e32 v5, 15, v25
	ds_read_b32 v2, v2
	ds_read_b32 v3, v3 offset:64
	ds_read_b32 v4, v4
	v_lshl_add_u32 v5, v5, 2, v36
	v_and_b32_e32 v8, 60, v8
	ds_read_b32 v5, v5 offset:64
	v_add_u32_e32 v6, v36, v6
	v_lshl_add_u32 v7, v7, 2, v36
	v_add_u32_e32 v8, v36, v8
	v_and_b32_e32 v9, 15, v19
	ds_read_b32 v6, v6
	ds_read_b32 v7, v7 offset:64
	ds_read_b32 v8, v8
	v_lshl_add_u32 v9, v9, 2, v36
	ds_read_b32 v9, v9 offset:64
	s_waitcnt lgkmcnt(6)
	v_and_b32_e32 v10, 0x7f, v3
	s_waitcnt lgkmcnt(5)
	v_lshlrev_b32_e32 v3, 7, v4
	s_waitcnt lgkmcnt(4)
	v_and_b32_e32 v5, 0x7f, v5
	v_and_b32_e32 v3, 0x3f80, v3
	v_lshlrev_b32_e32 v2, 7, v2
	v_or_b32_e32 v3, v3, v5
	s_waitcnt lgkmcnt(1)
	v_lshlrev_b32_e32 v5, 7, v8
	v_lshlrev_b32_e32 v6, 7, v6
	v_and_b32_e32 v2, 0x3f80, v2
	s_waitcnt lgkmcnt(0)
	v_and_b32_e32 v4, 0x7f, v9
	v_and_b32_e32 v7, 0x7f, v7
	v_and_b32_e32 v5, 0x3f80, v5
	v_and_b32_e32 v6, 0x3f80, v6
	v_or_b32_e32 v2, v2, v10
	v_or_b32_e32 v5, v5, v4
	v_or_b32_e32 v4, v6, v7
	global_store_dwordx4 v[22:23], v[2:5], off offset:48
	global_store_dwordx4 v[20:21], v[38:41], off
	global_store_dwordx4 v[22:23], v[32:35], off offset:16
	v_pk_mul_f32 v[4:5], v[16:17], v[18:19] op_sel_hi:[1,0]
	v_pk_mul_f32 v[2:3], v[12:13], v[18:19] op_sel_hi:[1,0]
	global_store_dwordx4 v[20:21], v[2:5], off offset:48
	s_branch .LBB0_21
